# mla output RMS-norm pass: 4 tokens in flight per wave (loads issued up front) instead of one load-wait-store per iteration
# baseline (speedup 1.0000x reference)
; DI unsigned pack2(float a, float b) { f32x2_t v = {a, b}; bf16x2_t r = __builtin_convertvector(v, bf16x2_t); return __builtin_bit_cast(unsigned, r); }
; DI float lo2f(unsigned u) { return __uint_as_float(u << 16); }
; DI float hi2f(unsigned u) { return __uint_as_float(u & 0xffff0000u); }
; DI float wave_sum(float v) { v = red8(v); v += dpp_f<0x140>(v); return xsum32(xsum16(v)); }
; DI int otid() { int t = threadIdx.x; asm volatile("" : "+v"(t)); return t; }
; DI void mla_out_phase(const Params& p, int l) {
;   const u16* OO = (const u16*)(p.ws + WS_OO);
;   u16* CC = (u16*)(p.ws + WS_CC);
;   const int tid_ = otid(); const int lane = tid_ & 63;
;   const int gw = (blockIdx.x * NTHR + tid_) >> 6, nw = (gridDim.x * NTHR) >> 6;
;   const float* on = p.out_norm + l * 512 + lane * 8;
;   const float4 w0 = *(const float4*)on, w1 = *(const float4*)(on + 4);
;   for (int t = gw; t < T; t += nw) {
;     const uint4 q = *(const uint4*)(OO + (size_t)t * 512 + lane * 8);
;     float v[8] = {lo2f(q.x), hi2f(q.x), lo2f(q.y), hi2f(q.y), lo2f(q.z), hi2f(q.z), lo2f(q.w), hi2f(q.w)};
;     float ss = 0.f;
; #pragma unroll
;     for (int i = 0; i < 8; ++i) ss += v[i] * v[i];
;     ss = wave_sum(ss);
;     const float rstd = rsqrtf(ss * (1.f / 512.f) + 1e-6f);
;     uint4 o;
;     o.x = pack2(v[0] * rstd * w0.x, v[1] * rstd * w0.y); o.y = pack2(v[2] * rstd * w0.z, v[3] * rstd * w0.w);
;     o.z = pack2(v[4] * rstd * w1.x, v[5] * rstd * w1.y); o.w = pack2(v[6] * rstd * w1.z, v[7] * rstd * w1.w);
;     *(uint4*)(CC + (size_t)t * 1024 + lane * 8) = o;
;   }
.Lmla4_top:
	v_readfirstlane_b32 s4, v10
	s_mul_i32 s5, s33, 3
	s_add_u32 s4, s4, s5
	s_cmp_gt_u32 s4, 0xffff
	s_cbranch_scc1 .Lmla4_rest
	v_lshl_add_u64 v[18:19], v[16:17], 0, v[12:13]
	v_add_co_u32_e32 v18, vcc, 0x34ac8000, v18
	s_nop 1
	v_addc_co_u32_e32 v19, vcc, 0, v19, vcc
	s_nop 0
	global_load_dwordx4 v[240:243], v[18:19], off
	v_lshl_add_u64 v[18:19], v[18:19], 0, s[30:31]
	global_load_dwordx4 v[244:247], v[18:19], off
	v_lshl_add_u64 v[18:19], v[18:19], 0, s[30:31]
	global_load_dwordx4 v[248:251], v[18:19], off
	v_lshl_add_u64 v[18:19], v[18:19], 0, s[30:31]
	global_load_dwordx4 v[252:255], v[18:19], off
	s_waitcnt vmcnt(3)
	v_lshlrev_b32_e32 v22, 16, v240
	v_and_b32_e32 v23, 0xffff0000, v240
	v_lshlrev_b32_e32 v24, 16, v241
	v_and_b32_e32 v25, 0xffff0000, v241
	v_pk_mul_f32 v[32:33], v[22:23], v[22:23]
	v_pk_mul_f32 v[30:31], v[24:25], v[24:25]
	v_add_f32_e32 v1, v32, v33
	v_lshlrev_b32_e32 v26, 16, v242
	v_and_b32_e32 v27, 0xffff0000, v242
	v_add_f32_e32 v1, v1, v30
	v_lshlrev_b32_e32 v28, 16, v243
	v_and_b32_e32 v29, 0xffff0000, v243
	v_pk_mul_f32 v[20:21], v[26:27], v[26:27]
	v_add_f32_e32 v1, v31, v1
	v_add_f32_e32 v1, v20, v1
	v_pk_mul_f32 v[18:19], v[28:29], v[28:29]
	v_add_f32_e32 v1, v21, v1
	v_add_f32_e32 v1, v18, v1
	v_add_f32_e32 v1, v19, v1
	s_nop 1
	v_add_f32_dpp v1, v1, v1 quad_perm:[1,0,3,2] row_mask:0xf bank_mask:0xf bound_ctrl:1
	s_nop 1
	v_add_f32_dpp v1, v1, v1 quad_perm:[2,3,0,1] row_mask:0xf bank_mask:0xf bound_ctrl:1
	s_nop 1
	v_add_f32_dpp v1, v1, v1 row_half_mirror row_mask:0xf bank_mask:0xf bound_ctrl:1
	s_nop 1
	v_add_f32_dpp v1, v1, v1 row_mirror row_mask:0xf bank_mask:0xf bound_ctrl:1
	v_mov_b32_e32 v11, v1
	s_nop 1
	v_permlane16_swap_b32_e32 v1, v11
	v_add_f32_e32 v1, v1, v11
	v_mov_b32_e32 v11, v1
	s_nop 1
	v_permlane32_swap_b32_e32 v1, v11
	v_add_f32_e32 v1, v1, v11
	v_fmamk_f32 v1, v1, 0x3b000000, v168
	v_cmp_gt_f32_e32 vcc, s51, v1
	v_mul_f32_e32 v11, 0x4b800000, v1
	s_nop 0
	v_cndmask_b32_e32 v1, v1, v11, vcc
	v_rsq_f32_e32 v1, v1
	s_nop 0
	v_mul_f32_e32 v11, 0x45800000, v1
	v_cndmask_b32_e32 v30, v1, v11, vcc
	v_pk_mul_f32 v[18:19], v[30:31], v[22:23] op_sel_hi:[0,1]
	v_pk_mul_f32 v[20:21], v[30:31], v[24:25] op_sel_hi:[0,1]
	v_pk_mul_f32 v[18:19], v[6:7], v[18:19]
	v_pk_mul_f32 v[20:21], v[8:9], v[20:21]
	v_cvt_pk_bf16_f32 v18, v18, v19
	v_cvt_pk_bf16_f32 v19, v20, v21
	v_pk_mul_f32 v[20:21], v[30:31], v[26:27] op_sel_hi:[0,1]
	v_pk_mul_f32 v[22:23], v[30:31], v[28:29] op_sel_hi:[0,1]
	v_pk_mul_f32 v[20:21], v[2:3], v[20:21]
	v_pk_mul_f32 v[22:23], v[4:5], v[22:23]
	v_cvt_pk_bf16_f32 v20, v20, v21
	v_cvt_pk_bf16_f32 v21, v22, v23
	v_lshl_add_u64 v[22:23], v[14:15], 0, v[12:13]
	v_add_co_u32_e32 v22, vcc, 0x2cac8000, v22
	v_lshl_add_u64 v[14:15], v[14:15], 0, s[22:23]
	s_nop 0
	v_addc_co_u32_e32 v23, vcc, 0, v23, vcc
	s_nop 0
	global_store_dwordx4 v[22:23], v[18:21], off
	v_lshl_add_u64 v[16:17], v[16:17], 0, s[30:31]
	v_add_u32_e32 v10, s33, v10
	s_nop 1
	s_waitcnt vmcnt(3)
	v_lshlrev_b32_e32 v22, 16, v244
	v_and_b32_e32 v23, 0xffff0000, v244
	v_lshlrev_b32_e32 v24, 16, v245
	v_and_b32_e32 v25, 0xffff0000, v245
	v_pk_mul_f32 v[32:33], v[22:23], v[22:23]
	v_pk_mul_f32 v[30:31], v[24:25], v[24:25]
	v_add_f32_e32 v1, v32, v33
	v_lshlrev_b32_e32 v26, 16, v246
	v_and_b32_e32 v27, 0xffff0000, v246
	v_add_f32_e32 v1, v1, v30
	v_lshlrev_b32_e32 v28, 16, v247
	v_and_b32_e32 v29, 0xffff0000, v247
	v_pk_mul_f32 v[20:21], v[26:27], v[26:27]
	v_add_f32_e32 v1, v31, v1
	v_add_f32_e32 v1, v20, v1
	v_pk_mul_f32 v[18:19], v[28:29], v[28:29]
	v_add_f32_e32 v1, v21, v1
	v_add_f32_e32 v1, v18, v1
	v_add_f32_e32 v1, v19, v1
	s_nop 1
	v_add_f32_dpp v1, v1, v1 quad_perm:[1,0,3,2] row_mask:0xf bank_mask:0xf bound_ctrl:1
	s_nop 1
	v_add_f32_dpp v1, v1, v1 quad_perm:[2,3,0,1] row_mask:0xf bank_mask:0xf bound_ctrl:1
	s_nop 1
	v_add_f32_dpp v1, v1, v1 row_half_mirror row_mask:0xf bank_mask:0xf bound_ctrl:1
	s_nop 1
	v_add_f32_dpp v1, v1, v1 row_mirror row_mask:0xf bank_mask:0xf bound_ctrl:1
	v_mov_b32_e32 v11, v1
	s_nop 1
	v_permlane16_swap_b32_e32 v1, v11
	v_add_f32_e32 v1, v1, v11
	v_mov_b32_e32 v11, v1
	s_nop 1
	v_permlane32_swap_b32_e32 v1, v11
	v_add_f32_e32 v1, v1, v11
	v_fmamk_f32 v1, v1, 0x3b000000, v168
	v_cmp_gt_f32_e32 vcc, s51, v1
	v_mul_f32_e32 v11, 0x4b800000, v1
	s_nop 0
	v_cndmask_b32_e32 v1, v1, v11, vcc
	v_rsq_f32_e32 v1, v1
	s_nop 0
	v_mul_f32_e32 v11, 0x45800000, v1
	v_cndmask_b32_e32 v30, v1, v11, vcc
	v_pk_mul_f32 v[18:19], v[30:31], v[22:23] op_sel_hi:[0,1]
	v_pk_mul_f32 v[20:21], v[30:31], v[24:25] op_sel_hi:[0,1]
	v_pk_mul_f32 v[18:19], v[6:7], v[18:19]
	v_pk_mul_f32 v[20:21], v[8:9], v[20:21]
	v_cvt_pk_bf16_f32 v18, v18, v19
	v_cvt_pk_bf16_f32 v19, v20, v21
	v_pk_mul_f32 v[20:21], v[30:31], v[26:27] op_sel_hi:[0,1]
	v_pk_mul_f32 v[22:23], v[30:31], v[28:29] op_sel_hi:[0,1]
	v_pk_mul_f32 v[20:21], v[2:3], v[20:21]
	v_pk_mul_f32 v[22:23], v[4:5], v[22:23]
	v_cvt_pk_bf16_f32 v20, v20, v21
	v_cvt_pk_bf16_f32 v21, v22, v23
	v_lshl_add_u64 v[22:23], v[14:15], 0, v[12:13]
	v_add_co_u32_e32 v22, vcc, 0x2cac8000, v22
	v_lshl_add_u64 v[14:15], v[14:15], 0, s[22:23]
	s_nop 0
	v_addc_co_u32_e32 v23, vcc, 0, v23, vcc
	s_nop 0
	global_store_dwordx4 v[22:23], v[18:21], off
	v_lshl_add_u64 v[16:17], v[16:17], 0, s[30:31]
	v_add_u32_e32 v10, s33, v10
	s_nop 1
	s_waitcnt vmcnt(3)
; DI unsigned pack2(float a, float b) { f32x2_t v = {a, b}; bf16x2_t r = __builtin_convertvector(v, bf16x2_t); return __builtin_bit_cast(unsigned, r); }
; DI float lo2f(unsigned u) { return __uint_as_float(u << 16); }
; DI float hi2f(unsigned u) { return __uint_as_float(u & 0xffff0000u); }
; DI float wave_sum(float v) { v = red8(v); v += dpp_f<0x140>(v); return xsum32(xsum16(v)); }
; DI void mla_out_phase(const Params& p, int l) {
;     ...
;   for (int t = gw; t < T; t += nw) {
;     const uint4 q = *(const uint4*)(OO + (size_t)t * 512 + lane * 8);
;     float v[8] = {lo2f(q.x), hi2f(q.x), lo2f(q.y), hi2f(q.y), lo2f(q.z), hi2f(q.z), lo2f(q.w), hi2f(q.w)};
;     float ss = 0.f;
; #pragma unroll
;     for (int i = 0; i < 8; ++i) ss += v[i] * v[i];
;     ss = wave_sum(ss);
;     const float rstd = rsqrtf(ss * (1.f / 512.f) + 1e-6f);
;     uint4 o;
;     o.x = pack2(v[0] * rstd * w0.x, v[1] * rstd * w0.y); o.y = pack2(v[2] * rstd * w0.z, v[3] * rstd * w0.w);
;     o.z = pack2(v[4] * rstd * w1.x, v[5] * rstd * w1.y); o.w = pack2(v[6] * rstd * w1.z, v[7] * rstd * w1.w);
;     *(uint4*)(CC + (size_t)t * 1024 + lane * 8) = o;
;   }
	v_lshlrev_b32_e32 v22, 16, v248
	v_and_b32_e32 v23, 0xffff0000, v248
	v_lshlrev_b32_e32 v24, 16, v249
	v_and_b32_e32 v25, 0xffff0000, v249
	v_pk_mul_f32 v[32:33], v[22:23], v[22:23]
	v_pk_mul_f32 v[30:31], v[24:25], v[24:25]
	v_add_f32_e32 v1, v32, v33
	v_lshlrev_b32_e32 v26, 16, v250
	v_and_b32_e32 v27, 0xffff0000, v250
	v_add_f32_e32 v1, v1, v30
	v_lshlrev_b32_e32 v28, 16, v251
	v_and_b32_e32 v29, 0xffff0000, v251
	v_pk_mul_f32 v[20:21], v[26:27], v[26:27]
	v_add_f32_e32 v1, v31, v1
	v_add_f32_e32 v1, v20, v1
	v_pk_mul_f32 v[18:19], v[28:29], v[28:29]
	v_add_f32_e32 v1, v21, v1
	v_add_f32_e32 v1, v18, v1
	v_add_f32_e32 v1, v19, v1
	s_nop 1
	v_add_f32_dpp v1, v1, v1 quad_perm:[1,0,3,2] row_mask:0xf bank_mask:0xf bound_ctrl:1
	s_nop 1
	v_add_f32_dpp v1, v1, v1 quad_perm:[2,3,0,1] row_mask:0xf bank_mask:0xf bound_ctrl:1
	s_nop 1
	v_add_f32_dpp v1, v1, v1 row_half_mirror row_mask:0xf bank_mask:0xf bound_ctrl:1
	s_nop 1
	v_add_f32_dpp v1, v1, v1 row_mirror row_mask:0xf bank_mask:0xf bound_ctrl:1
	v_mov_b32_e32 v11, v1
	s_nop 1
	v_permlane16_swap_b32_e32 v1, v11
	v_add_f32_e32 v1, v1, v11
	v_mov_b32_e32 v11, v1
	s_nop 1
	v_permlane32_swap_b32_e32 v1, v11
	v_add_f32_e32 v1, v1, v11
	v_fmamk_f32 v1, v1, 0x3b000000, v168
	v_cmp_gt_f32_e32 vcc, s51, v1
	v_mul_f32_e32 v11, 0x4b800000, v1
	s_nop 0
	v_cndmask_b32_e32 v1, v1, v11, vcc
	v_rsq_f32_e32 v1, v1
	s_nop 0
	v_mul_f32_e32 v11, 0x45800000, v1
	v_cndmask_b32_e32 v30, v1, v11, vcc
	v_pk_mul_f32 v[18:19], v[30:31], v[22:23] op_sel_hi:[0,1]
	v_pk_mul_f32 v[20:21], v[30:31], v[24:25] op_sel_hi:[0,1]
	v_pk_mul_f32 v[18:19], v[6:7], v[18:19]
	v_pk_mul_f32 v[20:21], v[8:9], v[20:21]
	v_cvt_pk_bf16_f32 v18, v18, v19
	v_cvt_pk_bf16_f32 v19, v20, v21
	v_pk_mul_f32 v[20:21], v[30:31], v[26:27] op_sel_hi:[0,1]
	v_pk_mul_f32 v[22:23], v[30:31], v[28:29] op_sel_hi:[0,1]
	v_pk_mul_f32 v[20:21], v[2:3], v[20:21]
	v_pk_mul_f32 v[22:23], v[4:5], v[22:23]
	v_cvt_pk_bf16_f32 v20, v20, v21
	v_cvt_pk_bf16_f32 v21, v22, v23
	v_lshl_add_u64 v[22:23], v[14:15], 0, v[12:13]
	v_add_co_u32_e32 v22, vcc, 0x2cac8000, v22
	v_lshl_add_u64 v[14:15], v[14:15], 0, s[22:23]
	s_nop 0
	v_addc_co_u32_e32 v23, vcc, 0, v23, vcc
	s_nop 0
	global_store_dwordx4 v[22:23], v[18:21], off
	v_lshl_add_u64 v[16:17], v[16:17], 0, s[30:31]
	v_add_u32_e32 v10, s33, v10
	s_nop 1
	s_waitcnt vmcnt(3)
	v_lshlrev_b32_e32 v22, 16, v252
	v_and_b32_e32 v23, 0xffff0000, v252
	v_lshlrev_b32_e32 v24, 16, v253
	v_and_b32_e32 v25, 0xffff0000, v253
	v_pk_mul_f32 v[32:33], v[22:23], v[22:23]
	v_pk_mul_f32 v[30:31], v[24:25], v[24:25]
	v_add_f32_e32 v1, v32, v33
	v_lshlrev_b32_e32 v26, 16, v254
	v_and_b32_e32 v27, 0xffff0000, v254
	v_add_f32_e32 v1, v1, v30
	v_lshlrev_b32_e32 v28, 16, v255
	v_and_b32_e32 v29, 0xffff0000, v255
	v_pk_mul_f32 v[20:21], v[26:27], v[26:27]
	v_add_f32_e32 v1, v31, v1
	v_add_f32_e32 v1, v20, v1
	v_pk_mul_f32 v[18:19], v[28:29], v[28:29]
	v_add_f32_e32 v1, v21, v1
	v_add_f32_e32 v1, v18, v1
	v_add_f32_e32 v1, v19, v1
	s_nop 1
	v_add_f32_dpp v1, v1, v1 quad_perm:[1,0,3,2] row_mask:0xf bank_mask:0xf bound_ctrl:1
	s_nop 1
	v_add_f32_dpp v1, v1, v1 quad_perm:[2,3,0,1] row_mask:0xf bank_mask:0xf bound_ctrl:1
	s_nop 1
	v_add_f32_dpp v1, v1, v1 row_half_mirror row_mask:0xf bank_mask:0xf bound_ctrl:1
	s_nop 1
	v_add_f32_dpp v1, v1, v1 row_mirror row_mask:0xf bank_mask:0xf bound_ctrl:1
	v_mov_b32_e32 v11, v1
	s_nop 1
	v_permlane16_swap_b32_e32 v1, v11
	v_add_f32_e32 v1, v1, v11
	v_mov_b32_e32 v11, v1
	s_nop 1
	v_permlane32_swap_b32_e32 v1, v11
	v_add_f32_e32 v1, v1, v11
	v_fmamk_f32 v1, v1, 0x3b000000, v168
	v_cmp_gt_f32_e32 vcc, s51, v1
	v_mul_f32_e32 v11, 0x4b800000, v1
	s_nop 0
	v_cndmask_b32_e32 v1, v1, v11, vcc
	v_rsq_f32_e32 v1, v1
	s_nop 0
	v_mul_f32_e32 v11, 0x45800000, v1
	v_cndmask_b32_e32 v30, v1, v11, vcc
	v_pk_mul_f32 v[18:19], v[30:31], v[22:23] op_sel_hi:[0,1]
	v_pk_mul_f32 v[20:21], v[30:31], v[24:25] op_sel_hi:[0,1]
	v_pk_mul_f32 v[18:19], v[6:7], v[18:19]
	v_pk_mul_f32 v[20:21], v[8:9], v[20:21]
	v_cvt_pk_bf16_f32 v18, v18, v19
	v_cvt_pk_bf16_f32 v19, v20, v21
	v_pk_mul_f32 v[20:21], v[30:31], v[26:27] op_sel_hi:[0,1]
	v_pk_mul_f32 v[22:23], v[30:31], v[28:29] op_sel_hi:[0,1]
	v_pk_mul_f32 v[20:21], v[2:3], v[20:21]
	v_pk_mul_f32 v[22:23], v[4:5], v[22:23]
	v_cvt_pk_bf16_f32 v20, v20, v21
	v_cvt_pk_bf16_f32 v21, v22, v23
	v_lshl_add_u64 v[22:23], v[14:15], 0, v[12:13]
	v_add_co_u32_e32 v22, vcc, 0x2cac8000, v22
	v_lshl_add_u64 v[14:15], v[14:15], 0, s[22:23]
	s_nop 0
	v_addc_co_u32_e32 v23, vcc, 0, v23, vcc
	s_nop 0
	global_store_dwordx4 v[22:23], v[18:21], off
	v_lshl_add_u64 v[16:17], v[16:17], 0, s[30:31]
	v_add_u32_e32 v10, s33, v10
	s_nop 1
	s_branch .Lmla4_top
.Lmla4_rest:
	v_readfirstlane_b32 s4, v10
	s_cmp_gt_u32 s4, 0xffff
	s_cbranch_scc1 .LBB0_568
